# S5 scan loop software-pipelined: set-A/set-B split scan, next chunk's bu MFMAs and previous chunk's H*Cm tail interleaved into the scan, running pointers, x2 unroll
# speedup vs baseline: 1.0346x; 1.0105x over previous
.LBB0_98:
	s_or_b64 exec, exec, s[2:3]
	v_or_b32_e32 v0, v2, v204
	v_lshlrev_b64 v[8:9], 12, v[0:1]
	s_mov_b64 s[2:3], 0x1000
	v_lshlrev_b64 v[6:7], 8, v[0:1]
	v_lshl_add_u64 v[8:9], v[8:9], 0, s[2:3]
	v_cndmask_b32_e64 v7, v9, v7, s[44:45]
	v_cndmask_b32_e64 v6, v8, v6, s[44:45]
	v_readlane_b32 s4, v252, 48
	v_lshlrev_b32_e32 v4, 4, v4
	v_lshlrev_b64 v[6:7], 12, v[6:7]
	v_readlane_b32 s18, v252, 62
	v_readlane_b32 s19, v252, 63
	v_ashrrev_i32_e32 v5, 31, v4
	v_add_u32_e32 v0, -16, v3
	v_lshl_add_u64 v[6:7], s[18:19], 0, v[6:7]
	v_lshlrev_b64 v[12:13], 2, v[4:5]
	v_cndmask_b32_e64 v0, v0, 0, s[40:41]
	v_lshl_add_u64 v[4:5], v[6:7], 0, v[12:13]
	v_mov_b32_e32 v149, v1
	v_or_b32_e32 v0, v0, v205
	v_lshl_add_u64 v[156:157], v[4:5], 0, v[148:149]
	v_lshlrev_b64 v[4:5], 12, v[0:1]
	v_subrev_u32_e32 v0, 32, v3
	v_cndmask_b32_e64 v0, v0, 16, s[40:41]
	v_or_b32_e32 v0, v0, v205
	s_waitcnt vmcnt(12)
	v_lshlrev_b64 v[14:15], 12, v[0:1]
	v_lshl_add_u64 v[8:9], v[156:157], 0, v[4:5]
	v_lshl_add_u64 v[14:15], v[156:157], 0, v[14:15]
	global_load_dwordx4 v[4:7], v[8:9], off offset:16
	s_nop 0
	global_load_dwordx4 v[8:11], v[8:9], off
	s_nop 0
	global_load_dwordx4 v[98:101], v[14:15], off offset:16
	global_load_dwordx4 v[102:105], v[14:15], off
	v_mov_b64_e32 v[248:249], v[14:15]
	v_lshrrev_b32_e32 v149, 4, v3
	v_subrev_u32_e32 v210, 48, v3
	v_mov_b32_e32 v3, v1
	v_lshlrev_b64 v[14:15], 12, v[2:3]
	v_lshl_add_u64 v[162:163], v[146:147], 0, v[12:13]
	v_lshlrev_b64 v[12:13], 8, v[2:3]
	v_or_b32_e32 v0, 0x1000, v14
	v_cndmask_b32_e64 v164, v0, v12, s[44:45]
	v_or_b32_e32 v0, 1, v2
	v_cndmask_b32_e64 v165, v15, v13, s[44:45]
	v_lshlrev_b64 v[12:13], 12, v[0:1]
	v_lshlrev_b64 v[2:3], 8, v[0:1]
	v_lshl_add_u64 v[12:13], v[12:13], 0, s[2:3]
	v_cndmask_b32_e64 v167, v13, v3, s[44:45]
	v_cndmask_b32_e64 v166, v12, v2, s[44:45]
	v_mov_b32_e32 v2, v1
	v_mov_b32_e32 v3, v1
	v_mov_b32_e32 v0, v1
	v_mov_b64_e32 v[108:109], v[2:3]
	v_mov_b64_e32 v[112:113], v[2:3]
	s_waitcnt vmcnt(5)
	v_pk_mov_b32 v[158:159], v[152:153], v[152:153] op_sel:[1,0]
	s_waitcnt vmcnt(4)
	v_pk_mov_b32 v[160:161], v[154:155], v[154:155] op_sel:[1,0]
	s_mov_b32 s28, 0
	s_mov_b32 s34, 32
	v_mov_b32_e32 v168, v152
	v_mov_b32_e32 v169, v152
	v_mov_b32_e32 v170, v153
	v_mov_b32_e32 v171, v153
	v_mov_b32_e32 v172, v154
	v_mov_b32_e32 v173, v154
	v_mov_b32_e32 v174, v155
	v_mov_b32_e32 v175, v155
	s_mov_b64 s[2:3], 0
	v_mov_b64_e32 v[106:107], v[0:1]
	v_mov_b64_e32 v[110:111], v[0:1]
	v_readlane_b32 s5, v252, 49
	v_readlane_b32 s6, v252, 50
	v_readlane_b32 s7, v252, 51
	v_readlane_b32 s8, v252, 52
	v_readlane_b32 s9, v252, 53
	v_readlane_b32 s10, v252, 54
	v_readlane_b32 s11, v252, 55
	v_readlane_b32 s12, v252, 56
	v_readlane_b32 s13, v252, 57
	v_readlane_b32 s14, v252, 58
	v_readlane_b32 s15, v252, 59
	v_readlane_b32 s16, v252, 60
	v_readlane_b32 s17, v252, 61
.LBB0_100:
	s_waitcnt vmcnt(0)
	v_readfirstlane_b32 s52, v149
	s_mov_b32 s50, 0x10000
	s_mov_b32 s51, 0
	s_mov_b32 s54, 0x1000
	s_mov_b32 s55, 0
	s_mov_b32 s56, 0x3000
	s_mov_b32 s57, 0
	v_add_u32_e32 v0, 32, v210
	v_cndmask_b32_e64 v0, v0, 0, s[40:41]
	v_or_b32_e32 v12, v0, v140
	v_ashrrev_i32_e32 v13, 31, v12
	v_cvt_pk_bf16_f32 v212, v8, v9
	v_cvt_pk_bf16_f32 v213, v10, v11
	v_cvt_pk_bf16_f32 v214, v4, v5
	v_cvt_pk_bf16_f32 v215, v6, v7
	v_lshl_add_u64 v[14:15], v[12:13], 0, v[164:165]
	v_lshlrev_b64 v[14:15], 12, v[14:15]
	v_mfma_f32_32x32x16_bf16 v[34:49], v[212:215], v[66:69], 0
	v_mfma_f32_32x32x16_bf16 v[50:65], v[212:215], v[74:77], 0
	v_lshl_add_u64 v[14:15], v[162:163], 0, v[14:15]
	v_lshl_add_u64 v[240:241], v[14:15], 0, s[54:55]
	v_lshl_add_u64 v[242:243], v[14:15], 0, s[56:57]
	v_lshl_add_u64 v[14:15], v[12:13], 0, v[166:167]
	v_lshlrev_b64 v[14:15], 12, v[14:15]
	v_lshl_add_u64 v[14:15], v[162:163], 0, v[14:15]
	v_lshl_add_u64 v[244:245], v[14:15], 0, s[54:55]
	v_lshl_add_u64 v[246:247], v[14:15], 0, s[56:57]
	s_nop 7
	s_cmp_lg_u64 s[40:41], 0
	s_cbranch_scc1 .LS5P_loopd0
	s_mov_b32 s50, 0xffff0000
	s_mov_b32 s51, -1
.LS5P_loopd1:
	s_add_u32 s20, s28, 2
	s_cmp_lt_u32 s20, s52
	s_cselect_b64 s[58:59], s[50:51], 0
	v_lshl_add_u64 v[248:249], v[248:249], 0, s[58:59]
	global_load_dwordx4 v[110:113], v[248:249], off offset:16
	global_load_dwordx4 v[106:109], v[248:249], off
	ds_read_b128 v[216:219], v208
	ds_read_b128 v[220:223], v208 offset:4352
	ds_read_b128 v[224:227], v208 offset:64
	ds_read_b128 v[228:231], v208 offset:4416
	v_fmac_f32_e32 v49, v152, v182
	v_fmac_f32_e32 v65, v152, v178
	v_fma_f32 v49, -v153, v178, v49
	v_fmac_f32_e32 v65, v153, v182
	v_mfma_f32_32x32x16_bf16 v[2:17], v[212:215], v[70:73], 0
	v_fmac_f32_e32 v48, v152, v49
	v_fmac_f32_e32 v64, v152, v65
	v_cvt_pk_bf16_f32 v184, v49, v65
	v_fma_f32 v48, -v153, v65, v48
	v_fmac_f32_e32 v64, v153, v49
	ds_write_b32 v207, v184 offset:4080
	v_fmac_f32_e32 v47, v152, v48
	v_fmac_f32_e32 v63, v152, v64
	v_cvt_pk_bf16_f32 v185, v48, v64
	v_fma_f32 v47, -v153, v64, v47
	v_fmac_f32_e32 v63, v153, v48
	ds_write_b32 v207, v185 offset:3808
	v_mfma_f32_32x32x16_bf16 v[18:33], v[212:215], v[78:81], 0
	v_fmac_f32_e32 v46, v152, v47
	v_fmac_f32_e32 v62, v152, v63
	v_cvt_pk_bf16_f32 v184, v47, v63
	v_fma_f32 v46, -v153, v63, v46
	v_fmac_f32_e32 v62, v153, v47
	ds_write_b32 v207, v184 offset:3536
	v_fmac_f32_e32 v45, v152, v46
	v_fmac_f32_e32 v61, v152, v62
	v_cvt_pk_bf16_f32 v185, v46, v62
	v_fma_f32 v45, -v153, v62, v45
	v_fmac_f32_e32 v61, v153, v46
	ds_write_b32 v207, v185 offset:3264
	s_waitcnt lgkmcnt(6)
	v_mfma_f32_16x16x32_bf16 v[232:235], v[216:219], v[82:85], 0
	v_fmac_f32_e32 v44, v152, v45
	v_fmac_f32_e32 v60, v152, v61
	v_cvt_pk_bf16_f32 v184, v45, v61
	v_fma_f32 v44, -v153, v61, v44
	v_fmac_f32_e32 v60, v153, v45
	ds_write_b32 v207, v184 offset:2992
	v_mfma_f32_16x16x32_bf16 v[236:239], v[220:223], v[82:85], 0
	v_fmac_f32_e32 v43, v152, v44
	v_fmac_f32_e32 v59, v152, v60
	v_cvt_pk_bf16_f32 v185, v44, v60
	v_fma_f32 v43, -v153, v60, v43
	v_fmac_f32_e32 v59, v153, v44
	ds_write_b32 v207, v185 offset:2720
	s_waitcnt lgkmcnt(6)
	v_mfma_f32_16x16x32_bf16 v[232:235], v[224:227], v[86:89], v[232:235]
	v_fmac_f32_e32 v42, v152, v43
	v_fmac_f32_e32 v58, v152, v59
	v_cvt_pk_bf16_f32 v184, v43, v59
	v_fma_f32 v42, -v153, v59, v42
	v_fmac_f32_e32 v58, v153, v43
	ds_write_b32 v207, v184 offset:2448
	v_mfma_f32_16x16x32_bf16 v[236:239], v[228:231], v[86:89], v[236:239]
	v_fmac_f32_e32 v41, v152, v42
	v_fmac_f32_e32 v57, v152, v58
	v_cvt_pk_bf16_f32 v185, v42, v58
	v_fma_f32 v41, -v153, v58, v41
	v_fmac_f32_e32 v57, v153, v42
	ds_write_b32 v207, v185 offset:2176
	ds_read_b128 v[216:219], v208 offset:128
	ds_read_b128 v[220:223], v208 offset:4480
	ds_read_b128 v[224:227], v208 offset:192
	ds_read_b128 v[228:231], v208 offset:4544
	v_fmac_f32_e32 v40, v152, v41
	v_fmac_f32_e32 v56, v152, v57
	v_cvt_pk_bf16_f32 v184, v41, v57
	v_fma_f32 v40, -v153, v57, v40
	v_fmac_f32_e32 v56, v153, v41
	ds_write_b32 v207, v184 offset:1904
	v_fmac_f32_e32 v39, v152, v40
	v_fmac_f32_e32 v55, v152, v56
	v_cvt_pk_bf16_f32 v185, v40, v56
	v_fma_f32 v39, -v153, v56, v39
	v_fmac_f32_e32 v55, v153, v40
	ds_write_b32 v207, v185 offset:1632
	v_fmac_f32_e32 v38, v152, v39
	v_fmac_f32_e32 v54, v152, v55
	v_cvt_pk_bf16_f32 v184, v39, v55
	v_fma_f32 v38, -v153, v55, v38
	v_fmac_f32_e32 v54, v153, v39
	ds_write_b32 v207, v184 offset:1360
	s_waitcnt lgkmcnt(5)
	v_mfma_f32_16x16x32_bf16 v[232:235], v[216:219], v[90:93], v[232:235]
	v_fmac_f32_e32 v37, v152, v38
	v_fmac_f32_e32 v53, v152, v54
	v_cvt_pk_bf16_f32 v185, v38, v54
	v_fma_f32 v37, -v153, v54, v37
	v_fmac_f32_e32 v53, v153, v38
	ds_write_b32 v207, v185 offset:1088
	v_mfma_f32_16x16x32_bf16 v[236:239], v[220:223], v[90:93], v[236:239]
	v_fmac_f32_e32 v36, v152, v37
	v_fmac_f32_e32 v52, v152, v53
	v_cvt_pk_bf16_f32 v184, v37, v53
	v_fma_f32 v36, -v153, v53, v36
	v_fmac_f32_e32 v52, v153, v37
	ds_write_b32 v207, v184 offset:816
	s_waitcnt lgkmcnt(5)
	v_mfma_f32_16x16x32_bf16 v[232:235], v[224:227], v[94:97], v[232:235]
	v_fmac_f32_e32 v35, v152, v36
	v_fmac_f32_e32 v51, v152, v52
	v_cvt_pk_bf16_f32 v185, v36, v52
	v_fma_f32 v35, -v153, v52, v35
	v_fmac_f32_e32 v51, v153, v36
	ds_write_b32 v207, v185 offset:544
	v_mfma_f32_16x16x32_bf16 v[236:239], v[228:231], v[94:97], v[236:239]
	v_fma_f32 v182, v152, v35, v34
	v_fma_f32 v178, v152, v51, v50
	v_cvt_pk_bf16_f32 v184, v35, v51
	v_fma_f32 v182, -v153, v51, v182
	v_fmac_f32_e32 v178, v153, v35
	ds_write_b32 v207, v184 offset:272
	v_cvt_pk_bf16_f32 v185, v182, v178
	ds_write_b32 v207, v185 offset:0
	s_cmp_eq_u32 s28, 0
	s_cbranch_scc1 .LS5P_nstd1e
	global_store_dword v[240:241], v232, off offset:-4096
	global_store_dword v[240:241], v233, off
	global_store_dword v[242:243], v234, off offset:-4096
	global_store_dword v[242:243], v235, off
	global_store_dword v[244:245], v236, off offset:-4096
	global_store_dword v[244:245], v237, off
	global_store_dword v[246:247], v238, off offset:-4096
	global_store_dword v[246:247], v239, off
	v_lshl_add_u64 v[240:241], v[240:241], 0, s[50:51]
	v_lshl_add_u64 v[242:243], v[242:243], 0, s[50:51]
	v_lshl_add_u64 v[244:245], v[244:245], 0, s[50:51]
	v_lshl_add_u64 v[246:247], v[246:247], 0, s[50:51]
.LS5P_nstd1e:
	s_waitcnt vmcnt(16)
	v_cvt_pk_bf16_f32 v212, v102, v103
	v_cvt_pk_bf16_f32 v213, v104, v105
	v_cvt_pk_bf16_f32 v214, v98, v99
	v_cvt_pk_bf16_f32 v215, v100, v101
	v_fmac_f32_e32 v17, v154, v180
	v_fmac_f32_e32 v33, v154, v176
	v_fma_f32 v17, -v155, v176, v17
	v_fmac_f32_e32 v33, v155, v180
	v_mfma_f32_32x32x16_bf16 v[34:49], v[212:215], v[66:69], 0
	v_fmac_f32_e32 v16, v154, v17
	v_fmac_f32_e32 v32, v154, v33
	v_cvt_pk_bf16_f32 v184, v17, v33
	v_fma_f32 v16, -v155, v33, v16
	v_fmac_f32_e32 v32, v155, v17
	ds_write_b32 v207, v184 offset:4208
	v_fmac_f32_e32 v15, v154, v16
	v_fmac_f32_e32 v31, v154, v32
	v_cvt_pk_bf16_f32 v185, v16, v32
	v_fma_f32 v15, -v155, v32, v15
	v_fmac_f32_e32 v31, v155, v16
	ds_write_b32 v207, v185 offset:3936
	v_mfma_f32_32x32x16_bf16 v[50:65], v[212:215], v[74:77], 0
	v_fmac_f32_e32 v14, v154, v15
	v_fmac_f32_e32 v30, v154, v31
	v_cvt_pk_bf16_f32 v184, v15, v31
	v_fma_f32 v14, -v155, v31, v14
	v_fmac_f32_e32 v30, v155, v15
	ds_write_b32 v207, v184 offset:3664
	v_fmac_f32_e32 v13, v154, v14
	v_fmac_f32_e32 v29, v154, v30
	v_cvt_pk_bf16_f32 v185, v14, v30
	v_fma_f32 v13, -v155, v30, v13
	v_fmac_f32_e32 v29, v155, v14
	ds_write_b32 v207, v185 offset:3392
	v_fmac_f32_e32 v12, v154, v13
	v_fmac_f32_e32 v28, v154, v29
	v_cvt_pk_bf16_f32 v184, v13, v29
	v_fma_f32 v12, -v155, v29, v12
	v_fmac_f32_e32 v28, v155, v13
	ds_write_b32 v207, v184 offset:3120
	v_fmac_f32_e32 v11, v154, v12
	v_fmac_f32_e32 v27, v154, v28
	v_cvt_pk_bf16_f32 v185, v12, v28
	v_fma_f32 v11, -v155, v28, v11
	v_fmac_f32_e32 v27, v155, v12
	ds_write_b32 v207, v185 offset:2848
	v_fmac_f32_e32 v10, v154, v11
	v_fmac_f32_e32 v26, v154, v27
	v_cvt_pk_bf16_f32 v184, v11, v27
	v_fma_f32 v10, -v155, v27, v10
	v_fmac_f32_e32 v26, v155, v11
	ds_write_b32 v207, v184 offset:2576
	v_fmac_f32_e32 v9, v154, v10
	v_fmac_f32_e32 v25, v154, v26
	v_cvt_pk_bf16_f32 v185, v10, v26
	v_fma_f32 v9, -v155, v26, v9
	v_fmac_f32_e32 v25, v155, v10
	ds_write_b32 v207, v185 offset:2304
	v_fmac_f32_e32 v8, v154, v9
	v_fmac_f32_e32 v24, v154, v25
	v_cvt_pk_bf16_f32 v184, v9, v25
	v_fma_f32 v8, -v155, v25, v8
	v_fmac_f32_e32 v24, v155, v9
	ds_write_b32 v207, v184 offset:2032
	v_fmac_f32_e32 v7, v154, v8
	v_fmac_f32_e32 v23, v154, v24
	v_cvt_pk_bf16_f32 v185, v8, v24
	v_fma_f32 v7, -v155, v24, v7
	v_fmac_f32_e32 v23, v155, v8
	ds_write_b32 v207, v185 offset:1760
	v_fmac_f32_e32 v6, v154, v7
	v_fmac_f32_e32 v22, v154, v23
	v_cvt_pk_bf16_f32 v184, v7, v23
	v_fma_f32 v6, -v155, v23, v6
	v_fmac_f32_e32 v22, v155, v7
	ds_write_b32 v207, v184 offset:1488
	v_fmac_f32_e32 v5, v154, v6
	v_fmac_f32_e32 v21, v154, v22
	v_cvt_pk_bf16_f32 v185, v6, v22
	v_fma_f32 v5, -v155, v22, v5
	v_fmac_f32_e32 v21, v155, v6
	ds_write_b32 v207, v185 offset:1216
	v_fmac_f32_e32 v4, v154, v5
	v_fmac_f32_e32 v20, v154, v21
	v_cvt_pk_bf16_f32 v184, v5, v21
	v_fma_f32 v4, -v155, v21, v4
	v_fmac_f32_e32 v20, v155, v5
	ds_write_b32 v207, v184 offset:944
	v_fmac_f32_e32 v3, v154, v4
	v_fmac_f32_e32 v19, v154, v20
	v_cvt_pk_bf16_f32 v185, v4, v20
	v_fma_f32 v3, -v155, v20, v3
	v_fmac_f32_e32 v19, v155, v4
	ds_write_b32 v207, v185 offset:672
	v_fma_f32 v180, v154, v3, v2
	v_fma_f32 v176, v154, v19, v18
	v_cvt_pk_bf16_f32 v184, v3, v19
	v_fma_f32 v180, -v155, v19, v180
	v_fmac_f32_e32 v176, v155, v3
	ds_write_b32 v207, v184 offset:400
	v_cvt_pk_bf16_f32 v185, v180, v176
	ds_write_b32 v207, v185 offset:128
	s_add_u32 s28, s28, 1
	s_add_u32 s20, s28, 2
	s_cmp_lt_u32 s20, s52
	s_cselect_b64 s[58:59], s[50:51], 0
	v_lshl_add_u64 v[248:249], v[248:249], 0, s[58:59]
	global_load_dwordx4 v[98:101], v[248:249], off offset:16
	global_load_dwordx4 v[102:105], v[248:249], off
	ds_read_b128 v[216:219], v208
	ds_read_b128 v[220:223], v208 offset:4352
	ds_read_b128 v[224:227], v208 offset:64
	ds_read_b128 v[228:231], v208 offset:4416
	v_fmac_f32_e32 v49, v152, v182
	v_fmac_f32_e32 v65, v152, v178
	v_fma_f32 v49, -v153, v178, v49
	v_fmac_f32_e32 v65, v153, v182
	v_mfma_f32_32x32x16_bf16 v[2:17], v[212:215], v[70:73], 0
	v_fmac_f32_e32 v48, v152, v49
	v_fmac_f32_e32 v64, v152, v65
	v_cvt_pk_bf16_f32 v184, v49, v65
	v_fma_f32 v48, -v153, v65, v48
	v_fmac_f32_e32 v64, v153, v49
	ds_write_b32 v207, v184 offset:4080
	v_fmac_f32_e32 v47, v152, v48
	v_fmac_f32_e32 v63, v152, v64
	v_cvt_pk_bf16_f32 v185, v48, v64
	v_fma_f32 v47, -v153, v64, v47
	v_fmac_f32_e32 v63, v153, v48
	ds_write_b32 v207, v185 offset:3808
	v_mfma_f32_32x32x16_bf16 v[18:33], v[212:215], v[78:81], 0
	v_fmac_f32_e32 v46, v152, v47
	v_fmac_f32_e32 v62, v152, v63
	v_cvt_pk_bf16_f32 v184, v47, v63
	v_fma_f32 v46, -v153, v63, v46
	v_fmac_f32_e32 v62, v153, v47
	ds_write_b32 v207, v184 offset:3536
	v_fmac_f32_e32 v45, v152, v46
	v_fmac_f32_e32 v61, v152, v62
	v_cvt_pk_bf16_f32 v185, v46, v62
	v_fma_f32 v45, -v153, v62, v45
	v_fmac_f32_e32 v61, v153, v46
	ds_write_b32 v207, v185 offset:3264
	s_waitcnt lgkmcnt(6)
	v_mfma_f32_16x16x32_bf16 v[232:235], v[216:219], v[82:85], 0
	v_fmac_f32_e32 v44, v152, v45
	v_fmac_f32_e32 v60, v152, v61
	v_cvt_pk_bf16_f32 v184, v45, v61
	v_fma_f32 v44, -v153, v61, v44
	v_fmac_f32_e32 v60, v153, v45
	ds_write_b32 v207, v184 offset:2992
	v_mfma_f32_16x16x32_bf16 v[236:239], v[220:223], v[82:85], 0
	v_fmac_f32_e32 v43, v152, v44
	v_fmac_f32_e32 v59, v152, v60
	v_cvt_pk_bf16_f32 v185, v44, v60
	v_fma_f32 v43, -v153, v60, v43
	v_fmac_f32_e32 v59, v153, v44
	ds_write_b32 v207, v185 offset:2720
	s_waitcnt lgkmcnt(6)
	v_mfma_f32_16x16x32_bf16 v[232:235], v[224:227], v[86:89], v[232:235]
	v_fmac_f32_e32 v42, v152, v43
	v_fmac_f32_e32 v58, v152, v59
	v_cvt_pk_bf16_f32 v184, v43, v59
	v_fma_f32 v42, -v153, v59, v42
	v_fmac_f32_e32 v58, v153, v43
	ds_write_b32 v207, v184 offset:2448
	v_mfma_f32_16x16x32_bf16 v[236:239], v[228:231], v[86:89], v[236:239]
	v_fmac_f32_e32 v41, v152, v42
	v_fmac_f32_e32 v57, v152, v58
	v_cvt_pk_bf16_f32 v185, v42, v58
	v_fma_f32 v41, -v153, v58, v41
	v_fmac_f32_e32 v57, v153, v42
	ds_write_b32 v207, v185 offset:2176
	ds_read_b128 v[216:219], v208 offset:128
	ds_read_b128 v[220:223], v208 offset:4480
	ds_read_b128 v[224:227], v208 offset:192
	ds_read_b128 v[228:231], v208 offset:4544
	v_fmac_f32_e32 v40, v152, v41
	v_fmac_f32_e32 v56, v152, v57
	v_cvt_pk_bf16_f32 v184, v41, v57
	v_fma_f32 v40, -v153, v57, v40
	v_fmac_f32_e32 v56, v153, v41
	ds_write_b32 v207, v184 offset:1904
	v_fmac_f32_e32 v39, v152, v40
	v_fmac_f32_e32 v55, v152, v56
	v_cvt_pk_bf16_f32 v185, v40, v56
	v_fma_f32 v39, -v153, v56, v39
	v_fmac_f32_e32 v55, v153, v40
	ds_write_b32 v207, v185 offset:1632
	v_fmac_f32_e32 v38, v152, v39
	v_fmac_f32_e32 v54, v152, v55
	v_cvt_pk_bf16_f32 v184, v39, v55
	v_fma_f32 v38, -v153, v55, v38
	v_fmac_f32_e32 v54, v153, v39
	ds_write_b32 v207, v184 offset:1360
	s_waitcnt lgkmcnt(5)
	v_mfma_f32_16x16x32_bf16 v[232:235], v[216:219], v[90:93], v[232:235]
	v_fmac_f32_e32 v37, v152, v38
	v_fmac_f32_e32 v53, v152, v54
	v_cvt_pk_bf16_f32 v185, v38, v54
	v_fma_f32 v37, -v153, v54, v37
	v_fmac_f32_e32 v53, v153, v38
	ds_write_b32 v207, v185 offset:1088
	v_mfma_f32_16x16x32_bf16 v[236:239], v[220:223], v[90:93], v[236:239]
	v_fmac_f32_e32 v36, v152, v37
	v_fmac_f32_e32 v52, v152, v53
	v_cvt_pk_bf16_f32 v184, v37, v53
	v_fma_f32 v36, -v153, v53, v36
	v_fmac_f32_e32 v52, v153, v37
	ds_write_b32 v207, v184 offset:816
	s_waitcnt lgkmcnt(5)
	v_mfma_f32_16x16x32_bf16 v[232:235], v[224:227], v[94:97], v[232:235]
	v_fmac_f32_e32 v35, v152, v36
	v_fmac_f32_e32 v51, v152, v52
	v_cvt_pk_bf16_f32 v185, v36, v52
	v_fma_f32 v35, -v153, v52, v35
	v_fmac_f32_e32 v51, v153, v36
	ds_write_b32 v207, v185 offset:544
	v_mfma_f32_16x16x32_bf16 v[236:239], v[228:231], v[94:97], v[236:239]
	v_fma_f32 v182, v152, v35, v34
	v_fma_f32 v178, v152, v51, v50
	v_cvt_pk_bf16_f32 v184, v35, v51
	v_fma_f32 v182, -v153, v51, v182
	v_fmac_f32_e32 v178, v153, v35
	ds_write_b32 v207, v184 offset:272
	v_cvt_pk_bf16_f32 v185, v182, v178
	ds_write_b32 v207, v185 offset:0
	global_store_dword v[240:241], v232, off offset:-4096
	global_store_dword v[240:241], v233, off
	global_store_dword v[242:243], v234, off offset:-4096
	global_store_dword v[242:243], v235, off
	global_store_dword v[244:245], v236, off offset:-4096
	global_store_dword v[244:245], v237, off
	global_store_dword v[246:247], v238, off offset:-4096
	global_store_dword v[246:247], v239, off
	v_lshl_add_u64 v[240:241], v[240:241], 0, s[50:51]
	v_lshl_add_u64 v[242:243], v[242:243], 0, s[50:51]
	v_lshl_add_u64 v[244:245], v[244:245], 0, s[50:51]
	v_lshl_add_u64 v[246:247], v[246:247], 0, s[50:51]
	s_cmp_eq_u32 s28, 1
	s_cbranch_scc0 .LS5P_wd1o
	s_waitcnt vmcnt(10)
.LS5P_wd1o:
	s_waitcnt vmcnt(16)
	v_cvt_pk_bf16_f32 v212, v106, v107
	v_cvt_pk_bf16_f32 v213, v108, v109
	v_cvt_pk_bf16_f32 v214, v110, v111
	v_cvt_pk_bf16_f32 v215, v112, v113
	v_fmac_f32_e32 v17, v154, v180
	v_fmac_f32_e32 v33, v154, v176
	v_fma_f32 v17, -v155, v176, v17
	v_fmac_f32_e32 v33, v155, v180
	v_mfma_f32_32x32x16_bf16 v[34:49], v[212:215], v[66:69], 0
	v_fmac_f32_e32 v16, v154, v17
	v_fmac_f32_e32 v32, v154, v33
	v_cvt_pk_bf16_f32 v184, v17, v33
	v_fma_f32 v16, -v155, v33, v16
	v_fmac_f32_e32 v32, v155, v17
	ds_write_b32 v207, v184 offset:4208
	v_fmac_f32_e32 v15, v154, v16
	v_fmac_f32_e32 v31, v154, v32
	v_cvt_pk_bf16_f32 v185, v16, v32
	v_fma_f32 v15, -v155, v32, v15
	v_fmac_f32_e32 v31, v155, v16
	ds_write_b32 v207, v185 offset:3936
	v_mfma_f32_32x32x16_bf16 v[50:65], v[212:215], v[74:77], 0
	v_fmac_f32_e32 v14, v154, v15
	v_fmac_f32_e32 v30, v154, v31
	v_cvt_pk_bf16_f32 v184, v15, v31
	v_fma_f32 v14, -v155, v31, v14
	v_fmac_f32_e32 v30, v155, v15
	ds_write_b32 v207, v184 offset:3664
	v_fmac_f32_e32 v13, v154, v14
	v_fmac_f32_e32 v29, v154, v30
	v_cvt_pk_bf16_f32 v185, v14, v30
	v_fma_f32 v13, -v155, v30, v13
	v_fmac_f32_e32 v29, v155, v14
	ds_write_b32 v207, v185 offset:3392
	v_fmac_f32_e32 v12, v154, v13
	v_fmac_f32_e32 v28, v154, v29
	v_cvt_pk_bf16_f32 v184, v13, v29
	v_fma_f32 v12, -v155, v29, v12
	v_fmac_f32_e32 v28, v155, v13
	ds_write_b32 v207, v184 offset:3120
	v_fmac_f32_e32 v11, v154, v12
	v_fmac_f32_e32 v27, v154, v28
	v_cvt_pk_bf16_f32 v185, v12, v28
	v_fma_f32 v11, -v155, v28, v11
	v_fmac_f32_e32 v27, v155, v12
	ds_write_b32 v207, v185 offset:2848
	v_fmac_f32_e32 v10, v154, v11
	v_fmac_f32_e32 v26, v154, v27
	v_cvt_pk_bf16_f32 v184, v11, v27
	v_fma_f32 v10, -v155, v27, v10
	v_fmac_f32_e32 v26, v155, v11
	ds_write_b32 v207, v184 offset:2576
	v_fmac_f32_e32 v9, v154, v10
	v_fmac_f32_e32 v25, v154, v26
	v_cvt_pk_bf16_f32 v185, v10, v26
	v_fma_f32 v9, -v155, v26, v9
	v_fmac_f32_e32 v25, v155, v10
	ds_write_b32 v207, v185 offset:2304
	v_fmac_f32_e32 v8, v154, v9
	v_fmac_f32_e32 v24, v154, v25
	v_cvt_pk_bf16_f32 v184, v9, v25
	v_fma_f32 v8, -v155, v25, v8
	v_fmac_f32_e32 v24, v155, v9
	ds_write_b32 v207, v184 offset:2032
	v_fmac_f32_e32 v7, v154, v8
	v_fmac_f32_e32 v23, v154, v24
	v_cvt_pk_bf16_f32 v185, v8, v24
	v_fma_f32 v7, -v155, v24, v7
	v_fmac_f32_e32 v23, v155, v8
	ds_write_b32 v207, v185 offset:1760
	v_fmac_f32_e32 v6, v154, v7
	v_fmac_f32_e32 v22, v154, v23
	v_cvt_pk_bf16_f32 v184, v7, v23
	v_fma_f32 v6, -v155, v23, v6
	v_fmac_f32_e32 v22, v155, v7
	ds_write_b32 v207, v184 offset:1488
	v_fmac_f32_e32 v5, v154, v6
	v_fmac_f32_e32 v21, v154, v22
	v_cvt_pk_bf16_f32 v185, v6, v22
	v_fma_f32 v5, -v155, v22, v5
	v_fmac_f32_e32 v21, v155, v6
	ds_write_b32 v207, v185 offset:1216
	v_fmac_f32_e32 v4, v154, v5
	v_fmac_f32_e32 v20, v154, v21
	v_cvt_pk_bf16_f32 v184, v5, v21
	v_fma_f32 v4, -v155, v21, v4
	v_fmac_f32_e32 v20, v155, v5
	ds_write_b32 v207, v184 offset:944
	v_fmac_f32_e32 v3, v154, v4
	v_fmac_f32_e32 v19, v154, v20
	v_cvt_pk_bf16_f32 v185, v4, v20
	v_fma_f32 v3, -v155, v20, v3
	v_fmac_f32_e32 v19, v155, v4
	ds_write_b32 v207, v185 offset:672
	v_fma_f32 v180, v154, v3, v2
	v_fma_f32 v176, v154, v19, v18
	v_cvt_pk_bf16_f32 v184, v3, v19
	v_fma_f32 v180, -v155, v19, v180
	v_fmac_f32_e32 v176, v155, v3
	ds_write_b32 v207, v184 offset:400
	v_cvt_pk_bf16_f32 v185, v180, v176
	ds_write_b32 v207, v185 offset:128
	s_add_u32 s28, s28, 1
	s_cmp_lt_u32 s28, s52
	s_cbranch_scc1 .LS5P_loopd1
	s_branch .LS5P_epi
.LS5P_loopd0:
	s_add_u32 s20, s28, 2
	s_cmp_lt_u32 s20, s52
	s_cselect_b64 s[58:59], s[50:51], 0
	v_lshl_add_u64 v[248:249], v[248:249], 0, s[58:59]
	global_load_dwordx4 v[110:113], v[248:249], off offset:16
	global_load_dwordx4 v[106:109], v[248:249], off
	ds_read_b128 v[216:219], v208
	ds_read_b128 v[220:223], v208 offset:4352
	ds_read_b128 v[224:227], v208 offset:64
	ds_read_b128 v[228:231], v208 offset:4416
	v_fmac_f32_e32 v34, v152, v182
	v_fmac_f32_e32 v50, v152, v178
	v_fma_f32 v34, -v153, v178, v34
	v_fmac_f32_e32 v50, v153, v182
	v_mfma_f32_32x32x16_bf16 v[2:17], v[212:215], v[70:73], 0
	v_fmac_f32_e32 v35, v152, v34
	v_fmac_f32_e32 v51, v152, v50
	v_cvt_pk_bf16_f32 v184, v34, v50
	v_fma_f32 v35, -v153, v50, v35
	v_fmac_f32_e32 v51, v153, v34
	ds_write_b32 v207, v184 offset:0
	v_fmac_f32_e32 v36, v152, v35
	v_fmac_f32_e32 v52, v152, v51
	v_cvt_pk_bf16_f32 v185, v35, v51
	v_fma_f32 v36, -v153, v51, v36
	v_fmac_f32_e32 v52, v153, v35
	ds_write_b32 v207, v185 offset:272
	v_mfma_f32_32x32x16_bf16 v[18:33], v[212:215], v[78:81], 0
	v_fmac_f32_e32 v37, v152, v36
	v_fmac_f32_e32 v53, v152, v52
	v_cvt_pk_bf16_f32 v184, v36, v52
	v_fma_f32 v37, -v153, v52, v37
	v_fmac_f32_e32 v53, v153, v36
	ds_write_b32 v207, v184 offset:544
	v_fmac_f32_e32 v38, v152, v37
	v_fmac_f32_e32 v54, v152, v53
	v_cvt_pk_bf16_f32 v185, v37, v53
	v_fma_f32 v38, -v153, v53, v38
	v_fmac_f32_e32 v54, v153, v37
	ds_write_b32 v207, v185 offset:816
	s_waitcnt lgkmcnt(6)
	v_mfma_f32_16x16x32_bf16 v[232:235], v[216:219], v[82:85], 0
	v_fmac_f32_e32 v39, v152, v38
	v_fmac_f32_e32 v55, v152, v54
	v_cvt_pk_bf16_f32 v184, v38, v54
	v_fma_f32 v39, -v153, v54, v39
	v_fmac_f32_e32 v55, v153, v38
	ds_write_b32 v207, v184 offset:1088
	v_mfma_f32_16x16x32_bf16 v[236:239], v[220:223], v[82:85], 0
	v_fmac_f32_e32 v40, v152, v39
	v_fmac_f32_e32 v56, v152, v55
	v_cvt_pk_bf16_f32 v185, v39, v55
	v_fma_f32 v40, -v153, v55, v40
	v_fmac_f32_e32 v56, v153, v39
	ds_write_b32 v207, v185 offset:1360
	s_waitcnt lgkmcnt(6)
	v_mfma_f32_16x16x32_bf16 v[232:235], v[224:227], v[86:89], v[232:235]
	v_fmac_f32_e32 v41, v152, v40
	v_fmac_f32_e32 v57, v152, v56
	v_cvt_pk_bf16_f32 v184, v40, v56
	v_fma_f32 v41, -v153, v56, v41
	v_fmac_f32_e32 v57, v153, v40
	ds_write_b32 v207, v184 offset:1632
	v_mfma_f32_16x16x32_bf16 v[236:239], v[228:231], v[86:89], v[236:239]
	v_fmac_f32_e32 v42, v152, v41
	v_fmac_f32_e32 v58, v152, v57
	v_cvt_pk_bf16_f32 v185, v41, v57
	v_fma_f32 v42, -v153, v57, v42
	v_fmac_f32_e32 v58, v153, v41
	ds_write_b32 v207, v185 offset:1904
	ds_read_b128 v[216:219], v208 offset:128
	ds_read_b128 v[220:223], v208 offset:4480
	ds_read_b128 v[224:227], v208 offset:192
	ds_read_b128 v[228:231], v208 offset:4544
	v_fmac_f32_e32 v43, v152, v42
	v_fmac_f32_e32 v59, v152, v58
	v_cvt_pk_bf16_f32 v184, v42, v58
	v_fma_f32 v43, -v153, v58, v43
	v_fmac_f32_e32 v59, v153, v42
	ds_write_b32 v207, v184 offset:2176
	v_fmac_f32_e32 v44, v152, v43
	v_fmac_f32_e32 v60, v152, v59
	v_cvt_pk_bf16_f32 v185, v43, v59
	v_fma_f32 v44, -v153, v59, v44
	v_fmac_f32_e32 v60, v153, v43
	ds_write_b32 v207, v185 offset:2448
	v_fmac_f32_e32 v45, v152, v44
	v_fmac_f32_e32 v61, v152, v60
	v_cvt_pk_bf16_f32 v184, v44, v60
	v_fma_f32 v45, -v153, v60, v45
	v_fmac_f32_e32 v61, v153, v44
	ds_write_b32 v207, v184 offset:2720
	s_waitcnt lgkmcnt(5)
	v_mfma_f32_16x16x32_bf16 v[232:235], v[216:219], v[90:93], v[232:235]
	v_fmac_f32_e32 v46, v152, v45
	v_fmac_f32_e32 v62, v152, v61
	v_cvt_pk_bf16_f32 v185, v45, v61
	v_fma_f32 v46, -v153, v61, v46
	v_fmac_f32_e32 v62, v153, v45
	ds_write_b32 v207, v185 offset:2992
	v_mfma_f32_16x16x32_bf16 v[236:239], v[220:223], v[90:93], v[236:239]
	v_fmac_f32_e32 v47, v152, v46
	v_fmac_f32_e32 v63, v152, v62
	v_cvt_pk_bf16_f32 v184, v46, v62
	v_fma_f32 v47, -v153, v62, v47
	v_fmac_f32_e32 v63, v153, v46
	ds_write_b32 v207, v184 offset:3264
	s_waitcnt lgkmcnt(5)
	v_mfma_f32_16x16x32_bf16 v[232:235], v[224:227], v[94:97], v[232:235]
	v_fmac_f32_e32 v48, v152, v47
	v_fmac_f32_e32 v64, v152, v63
	v_cvt_pk_bf16_f32 v185, v47, v63
	v_fma_f32 v48, -v153, v63, v48
	v_fmac_f32_e32 v64, v153, v47
	ds_write_b32 v207, v185 offset:3536
	v_mfma_f32_16x16x32_bf16 v[236:239], v[228:231], v[94:97], v[236:239]
	v_fma_f32 v182, v152, v48, v49
	v_fma_f32 v178, v152, v64, v65
	v_cvt_pk_bf16_f32 v184, v48, v64
	v_fma_f32 v182, -v153, v64, v182
	v_fmac_f32_e32 v178, v153, v48
	ds_write_b32 v207, v184 offset:3808
	v_cvt_pk_bf16_f32 v185, v182, v178
	ds_write_b32 v207, v185 offset:4080
	s_cmp_eq_u32 s28, 0
	s_cbranch_scc1 .LS5P_nstd0e
	global_store_dword v[240:241], v232, off offset:-4096
	global_store_dword v[240:241], v233, off
	global_store_dword v[242:243], v234, off offset:-4096
	global_store_dword v[242:243], v235, off
	global_store_dword v[244:245], v236, off offset:-4096
	global_store_dword v[244:245], v237, off
	global_store_dword v[246:247], v238, off offset:-4096
	global_store_dword v[246:247], v239, off
	v_lshl_add_u64 v[240:241], v[240:241], 0, s[50:51]
	v_lshl_add_u64 v[242:243], v[242:243], 0, s[50:51]
	v_lshl_add_u64 v[244:245], v[244:245], 0, s[50:51]
	v_lshl_add_u64 v[246:247], v[246:247], 0, s[50:51]
.LS5P_nstd0e:
	s_waitcnt vmcnt(16)
	v_cvt_pk_bf16_f32 v212, v102, v103
	v_cvt_pk_bf16_f32 v213, v104, v105
	v_cvt_pk_bf16_f32 v214, v98, v99
	v_cvt_pk_bf16_f32 v215, v100, v101
	v_fmac_f32_e32 v2, v154, v180
	v_fmac_f32_e32 v18, v154, v176
	v_fma_f32 v2, -v155, v176, v2
	v_fmac_f32_e32 v18, v155, v180
	v_mfma_f32_32x32x16_bf16 v[34:49], v[212:215], v[66:69], 0
	v_fmac_f32_e32 v3, v154, v2
	v_fmac_f32_e32 v19, v154, v18
	v_cvt_pk_bf16_f32 v184, v2, v18
	v_fma_f32 v3, -v155, v18, v3
	v_fmac_f32_e32 v19, v155, v2
	ds_write_b32 v207, v184 offset:128
	v_fmac_f32_e32 v4, v154, v3
	v_fmac_f32_e32 v20, v154, v19
	v_cvt_pk_bf16_f32 v185, v3, v19
	v_fma_f32 v4, -v155, v19, v4
	v_fmac_f32_e32 v20, v155, v3
	ds_write_b32 v207, v185 offset:400
	v_mfma_f32_32x32x16_bf16 v[50:65], v[212:215], v[74:77], 0
	v_fmac_f32_e32 v5, v154, v4
	v_fmac_f32_e32 v21, v154, v20
	v_cvt_pk_bf16_f32 v184, v4, v20
	v_fma_f32 v5, -v155, v20, v5
	v_fmac_f32_e32 v21, v155, v4
	ds_write_b32 v207, v184 offset:672
	v_fmac_f32_e32 v6, v154, v5
	v_fmac_f32_e32 v22, v154, v21
	v_cvt_pk_bf16_f32 v185, v5, v21
	v_fma_f32 v6, -v155, v21, v6
	v_fmac_f32_e32 v22, v155, v5
	ds_write_b32 v207, v185 offset:944
	v_fmac_f32_e32 v7, v154, v6
	v_fmac_f32_e32 v23, v154, v22
	v_cvt_pk_bf16_f32 v184, v6, v22
	v_fma_f32 v7, -v155, v22, v7
	v_fmac_f32_e32 v23, v155, v6
	ds_write_b32 v207, v184 offset:1216
	v_fmac_f32_e32 v8, v154, v7
	v_fmac_f32_e32 v24, v154, v23
	v_cvt_pk_bf16_f32 v185, v7, v23
	v_fma_f32 v8, -v155, v23, v8
	v_fmac_f32_e32 v24, v155, v7
	ds_write_b32 v207, v185 offset:1488
	v_fmac_f32_e32 v9, v154, v8
	v_fmac_f32_e32 v25, v154, v24
	v_cvt_pk_bf16_f32 v184, v8, v24
	v_fma_f32 v9, -v155, v24, v9
	v_fmac_f32_e32 v25, v155, v8
	ds_write_b32 v207, v184 offset:1760
	v_fmac_f32_e32 v10, v154, v9
	v_fmac_f32_e32 v26, v154, v25
	v_cvt_pk_bf16_f32 v185, v9, v25
	v_fma_f32 v10, -v155, v25, v10
	v_fmac_f32_e32 v26, v155, v9
	ds_write_b32 v207, v185 offset:2032
	v_fmac_f32_e32 v11, v154, v10
	v_fmac_f32_e32 v27, v154, v26
	v_cvt_pk_bf16_f32 v184, v10, v26
	v_fma_f32 v11, -v155, v26, v11
	v_fmac_f32_e32 v27, v155, v10
	ds_write_b32 v207, v184 offset:2304
	v_fmac_f32_e32 v12, v154, v11
	v_fmac_f32_e32 v28, v154, v27
	v_cvt_pk_bf16_f32 v185, v11, v27
	v_fma_f32 v12, -v155, v27, v12
	v_fmac_f32_e32 v28, v155, v11
	ds_write_b32 v207, v185 offset:2576
	v_fmac_f32_e32 v13, v154, v12
	v_fmac_f32_e32 v29, v154, v28
	v_cvt_pk_bf16_f32 v184, v12, v28
	v_fma_f32 v13, -v155, v28, v13
	v_fmac_f32_e32 v29, v155, v12
	ds_write_b32 v207, v184 offset:2848
	v_fmac_f32_e32 v14, v154, v13
	v_fmac_f32_e32 v30, v154, v29
	v_cvt_pk_bf16_f32 v185, v13, v29
	v_fma_f32 v14, -v155, v29, v14
	v_fmac_f32_e32 v30, v155, v13
	ds_write_b32 v207, v185 offset:3120
	v_fmac_f32_e32 v15, v154, v14
	v_fmac_f32_e32 v31, v154, v30
	v_cvt_pk_bf16_f32 v184, v14, v30
	v_fma_f32 v15, -v155, v30, v15
	v_fmac_f32_e32 v31, v155, v14
	ds_write_b32 v207, v184 offset:3392
	v_fmac_f32_e32 v16, v154, v15
	v_fmac_f32_e32 v32, v154, v31
	v_cvt_pk_bf16_f32 v185, v15, v31
	v_fma_f32 v16, -v155, v31, v16
	v_fmac_f32_e32 v32, v155, v15
	ds_write_b32 v207, v185 offset:3664
	v_fma_f32 v180, v154, v16, v17
	v_fma_f32 v176, v154, v32, v33
	v_cvt_pk_bf16_f32 v184, v16, v32
	v_fma_f32 v180, -v155, v32, v180
	v_fmac_f32_e32 v176, v155, v16
	ds_write_b32 v207, v184 offset:3936
	v_cvt_pk_bf16_f32 v185, v180, v176
	ds_write_b32 v207, v185 offset:4208
	s_add_u32 s28, s28, 1
	s_add_u32 s20, s28, 2
	s_cmp_lt_u32 s20, s52
	s_cselect_b64 s[58:59], s[50:51], 0
	v_lshl_add_u64 v[248:249], v[248:249], 0, s[58:59]
	global_load_dwordx4 v[98:101], v[248:249], off offset:16
	global_load_dwordx4 v[102:105], v[248:249], off
	ds_read_b128 v[216:219], v208
	ds_read_b128 v[220:223], v208 offset:4352
	ds_read_b128 v[224:227], v208 offset:64
	ds_read_b128 v[228:231], v208 offset:4416
	v_fmac_f32_e32 v34, v152, v182
	v_fmac_f32_e32 v50, v152, v178
	v_fma_f32 v34, -v153, v178, v34
	v_fmac_f32_e32 v50, v153, v182
	v_mfma_f32_32x32x16_bf16 v[2:17], v[212:215], v[70:73], 0
	v_fmac_f32_e32 v35, v152, v34
	v_fmac_f32_e32 v51, v152, v50
	v_cvt_pk_bf16_f32 v184, v34, v50
	v_fma_f32 v35, -v153, v50, v35
	v_fmac_f32_e32 v51, v153, v34
	ds_write_b32 v207, v184 offset:0
	v_fmac_f32_e32 v36, v152, v35
	v_fmac_f32_e32 v52, v152, v51
	v_cvt_pk_bf16_f32 v185, v35, v51
	v_fma_f32 v36, -v153, v51, v36
	v_fmac_f32_e32 v52, v153, v35
	ds_write_b32 v207, v185 offset:272
	v_mfma_f32_32x32x16_bf16 v[18:33], v[212:215], v[78:81], 0
	v_fmac_f32_e32 v37, v152, v36
	v_fmac_f32_e32 v53, v152, v52
	v_cvt_pk_bf16_f32 v184, v36, v52
	v_fma_f32 v37, -v153, v52, v37
	v_fmac_f32_e32 v53, v153, v36
	ds_write_b32 v207, v184 offset:544
	v_fmac_f32_e32 v38, v152, v37
	v_fmac_f32_e32 v54, v152, v53
	v_cvt_pk_bf16_f32 v185, v37, v53
	v_fma_f32 v38, -v153, v53, v38
	v_fmac_f32_e32 v54, v153, v37
	ds_write_b32 v207, v185 offset:816
	s_waitcnt lgkmcnt(6)
	v_mfma_f32_16x16x32_bf16 v[232:235], v[216:219], v[82:85], 0
	v_fmac_f32_e32 v39, v152, v38
	v_fmac_f32_e32 v55, v152, v54
	v_cvt_pk_bf16_f32 v184, v38, v54
	v_fma_f32 v39, -v153, v54, v39
	v_fmac_f32_e32 v55, v153, v38
	ds_write_b32 v207, v184 offset:1088
	v_mfma_f32_16x16x32_bf16 v[236:239], v[220:223], v[82:85], 0
	v_fmac_f32_e32 v40, v152, v39
	v_fmac_f32_e32 v56, v152, v55
	v_cvt_pk_bf16_f32 v185, v39, v55
	v_fma_f32 v40, -v153, v55, v40
	v_fmac_f32_e32 v56, v153, v39
	ds_write_b32 v207, v185 offset:1360
	s_waitcnt lgkmcnt(6)
	v_mfma_f32_16x16x32_bf16 v[232:235], v[224:227], v[86:89], v[232:235]
	v_fmac_f32_e32 v41, v152, v40
	v_fmac_f32_e32 v57, v152, v56
	v_cvt_pk_bf16_f32 v184, v40, v56
	v_fma_f32 v41, -v153, v56, v41
	v_fmac_f32_e32 v57, v153, v40
	ds_write_b32 v207, v184 offset:1632
	v_mfma_f32_16x16x32_bf16 v[236:239], v[228:231], v[86:89], v[236:239]
	v_fmac_f32_e32 v42, v152, v41
	v_fmac_f32_e32 v58, v152, v57
	v_cvt_pk_bf16_f32 v185, v41, v57
	v_fma_f32 v42, -v153, v57, v42
	v_fmac_f32_e32 v58, v153, v41
	ds_write_b32 v207, v185 offset:1904
	ds_read_b128 v[216:219], v208 offset:128
	ds_read_b128 v[220:223], v208 offset:4480
	ds_read_b128 v[224:227], v208 offset:192
	ds_read_b128 v[228:231], v208 offset:4544
	v_fmac_f32_e32 v43, v152, v42
	v_fmac_f32_e32 v59, v152, v58
	v_cvt_pk_bf16_f32 v184, v42, v58
	v_fma_f32 v43, -v153, v58, v43
	v_fmac_f32_e32 v59, v153, v42
	ds_write_b32 v207, v184 offset:2176
	v_fmac_f32_e32 v44, v152, v43
	v_fmac_f32_e32 v60, v152, v59
	v_cvt_pk_bf16_f32 v185, v43, v59
	v_fma_f32 v44, -v153, v59, v44
	v_fmac_f32_e32 v60, v153, v43
	ds_write_b32 v207, v185 offset:2448
	v_fmac_f32_e32 v45, v152, v44
	v_fmac_f32_e32 v61, v152, v60
	v_cvt_pk_bf16_f32 v184, v44, v60
	v_fma_f32 v45, -v153, v60, v45
	v_fmac_f32_e32 v61, v153, v44
	ds_write_b32 v207, v184 offset:2720
	s_waitcnt lgkmcnt(5)
	v_mfma_f32_16x16x32_bf16 v[232:235], v[216:219], v[90:93], v[232:235]
	v_fmac_f32_e32 v46, v152, v45
	v_fmac_f32_e32 v62, v152, v61
	v_cvt_pk_bf16_f32 v185, v45, v61
	v_fma_f32 v46, -v153, v61, v46
	v_fmac_f32_e32 v62, v153, v45
	ds_write_b32 v207, v185 offset:2992
	v_mfma_f32_16x16x32_bf16 v[236:239], v[220:223], v[90:93], v[236:239]
	v_fmac_f32_e32 v47, v152, v46
	v_fmac_f32_e32 v63, v152, v62
	v_cvt_pk_bf16_f32 v184, v46, v62
	v_fma_f32 v47, -v153, v62, v47
	v_fmac_f32_e32 v63, v153, v46
	ds_write_b32 v207, v184 offset:3264
	s_waitcnt lgkmcnt(5)
	v_mfma_f32_16x16x32_bf16 v[232:235], v[224:227], v[94:97], v[232:235]
	v_fmac_f32_e32 v48, v152, v47
	v_fmac_f32_e32 v64, v152, v63
	v_cvt_pk_bf16_f32 v185, v47, v63
	v_fma_f32 v48, -v153, v63, v48
	v_fmac_f32_e32 v64, v153, v47
	ds_write_b32 v207, v185 offset:3536
	v_mfma_f32_16x16x32_bf16 v[236:239], v[228:231], v[94:97], v[236:239]
	v_fma_f32 v182, v152, v48, v49
	v_fma_f32 v178, v152, v64, v65
	v_cvt_pk_bf16_f32 v184, v48, v64
	v_fma_f32 v182, -v153, v64, v182
	v_fmac_f32_e32 v178, v153, v48
	ds_write_b32 v207, v184 offset:3808
	v_cvt_pk_bf16_f32 v185, v182, v178
	ds_write_b32 v207, v185 offset:4080
	global_store_dword v[240:241], v232, off offset:-4096
	global_store_dword v[240:241], v233, off
	global_store_dword v[242:243], v234, off offset:-4096
	global_store_dword v[242:243], v235, off
	global_store_dword v[244:245], v236, off offset:-4096
	global_store_dword v[244:245], v237, off
	global_store_dword v[246:247], v238, off offset:-4096
	global_store_dword v[246:247], v239, off
	v_lshl_add_u64 v[240:241], v[240:241], 0, s[50:51]
	v_lshl_add_u64 v[242:243], v[242:243], 0, s[50:51]
	v_lshl_add_u64 v[244:245], v[244:245], 0, s[50:51]
	v_lshl_add_u64 v[246:247], v[246:247], 0, s[50:51]
	s_cmp_eq_u32 s28, 1
	s_cbranch_scc0 .LS5P_wd0o
	s_waitcnt vmcnt(10)
.LS5P_wd0o:
	s_waitcnt vmcnt(16)
	v_cvt_pk_bf16_f32 v212, v106, v107
	v_cvt_pk_bf16_f32 v213, v108, v109
	v_cvt_pk_bf16_f32 v214, v110, v111
	v_cvt_pk_bf16_f32 v215, v112, v113
	v_fmac_f32_e32 v2, v154, v180
	v_fmac_f32_e32 v18, v154, v176
	v_fma_f32 v2, -v155, v176, v2
	v_fmac_f32_e32 v18, v155, v180
	v_mfma_f32_32x32x16_bf16 v[34:49], v[212:215], v[66:69], 0
	v_fmac_f32_e32 v3, v154, v2
	v_fmac_f32_e32 v19, v154, v18
	v_cvt_pk_bf16_f32 v184, v2, v18
	v_fma_f32 v3, -v155, v18, v3
	v_fmac_f32_e32 v19, v155, v2
	ds_write_b32 v207, v184 offset:128
	v_fmac_f32_e32 v4, v154, v3
	v_fmac_f32_e32 v20, v154, v19
	v_cvt_pk_bf16_f32 v185, v3, v19
	v_fma_f32 v4, -v155, v19, v4
	v_fmac_f32_e32 v20, v155, v3
	ds_write_b32 v207, v185 offset:400
	v_mfma_f32_32x32x16_bf16 v[50:65], v[212:215], v[74:77], 0
	v_fmac_f32_e32 v5, v154, v4
	v_fmac_f32_e32 v21, v154, v20
	v_cvt_pk_bf16_f32 v184, v4, v20
	v_fma_f32 v5, -v155, v20, v5
	v_fmac_f32_e32 v21, v155, v4
	ds_write_b32 v207, v184 offset:672
	v_fmac_f32_e32 v6, v154, v5
	v_fmac_f32_e32 v22, v154, v21
	v_cvt_pk_bf16_f32 v185, v5, v21
	v_fma_f32 v6, -v155, v21, v6
	v_fmac_f32_e32 v22, v155, v5
	ds_write_b32 v207, v185 offset:944
	v_fmac_f32_e32 v7, v154, v6
	v_fmac_f32_e32 v23, v154, v22
	v_cvt_pk_bf16_f32 v184, v6, v22
	v_fma_f32 v7, -v155, v22, v7
	v_fmac_f32_e32 v23, v155, v6
	ds_write_b32 v207, v184 offset:1216
	v_fmac_f32_e32 v8, v154, v7
	v_fmac_f32_e32 v24, v154, v23
	v_cvt_pk_bf16_f32 v185, v7, v23
	v_fma_f32 v8, -v155, v23, v8
	v_fmac_f32_e32 v24, v155, v7
	ds_write_b32 v207, v185 offset:1488
	v_fmac_f32_e32 v9, v154, v8
	v_fmac_f32_e32 v25, v154, v24
	v_cvt_pk_bf16_f32 v184, v8, v24
	v_fma_f32 v9, -v155, v24, v9
	v_fmac_f32_e32 v25, v155, v8
	ds_write_b32 v207, v184 offset:1760
	v_fmac_f32_e32 v10, v154, v9
	v_fmac_f32_e32 v26, v154, v25
	v_cvt_pk_bf16_f32 v185, v9, v25
	v_fma_f32 v10, -v155, v25, v10
	v_fmac_f32_e32 v26, v155, v9
	ds_write_b32 v207, v185 offset:2032
	v_fmac_f32_e32 v11, v154, v10
	v_fmac_f32_e32 v27, v154, v26
	v_cvt_pk_bf16_f32 v184, v10, v26
	v_fma_f32 v11, -v155, v26, v11
	v_fmac_f32_e32 v27, v155, v10
	ds_write_b32 v207, v184 offset:2304
	v_fmac_f32_e32 v12, v154, v11
	v_fmac_f32_e32 v28, v154, v27
	v_cvt_pk_bf16_f32 v185, v11, v27
	v_fma_f32 v12, -v155, v27, v12
	v_fmac_f32_e32 v28, v155, v11
	ds_write_b32 v207, v185 offset:2576
	v_fmac_f32_e32 v13, v154, v12
	v_fmac_f32_e32 v29, v154, v28
	v_cvt_pk_bf16_f32 v184, v12, v28
	v_fma_f32 v13, -v155, v28, v13
	v_fmac_f32_e32 v29, v155, v12
	ds_write_b32 v207, v184 offset:2848
	v_fmac_f32_e32 v14, v154, v13
	v_fmac_f32_e32 v30, v154, v29
	v_cvt_pk_bf16_f32 v185, v13, v29
	v_fma_f32 v14, -v155, v29, v14
	v_fmac_f32_e32 v30, v155, v13
	ds_write_b32 v207, v185 offset:3120
	v_fmac_f32_e32 v15, v154, v14
	v_fmac_f32_e32 v31, v154, v30
	v_cvt_pk_bf16_f32 v184, v14, v30
	v_fma_f32 v15, -v155, v30, v15
	v_fmac_f32_e32 v31, v155, v14
	ds_write_b32 v207, v184 offset:3392
	v_fmac_f32_e32 v16, v154, v15
	v_fmac_f32_e32 v32, v154, v31
	v_cvt_pk_bf16_f32 v185, v15, v31
	v_fma_f32 v16, -v155, v31, v16
	v_fmac_f32_e32 v32, v155, v15
	ds_write_b32 v207, v185 offset:3664
	v_fma_f32 v180, v154, v16, v17
	v_fma_f32 v176, v154, v32, v33
	v_cvt_pk_bf16_f32 v184, v16, v32
	v_fma_f32 v180, -v155, v32, v180
	v_fmac_f32_e32 v176, v155, v16
	ds_write_b32 v207, v184 offset:3936
	v_cvt_pk_bf16_f32 v185, v180, v176
	ds_write_b32 v207, v185 offset:4208
	s_add_u32 s28, s28, 1
	s_cmp_lt_u32 s28, s52
	s_cbranch_scc1 .LS5P_loopd0
.LS5P_epi:
	ds_read_b128 v[216:219], v208
	ds_read_b128 v[220:223], v208 offset:4352
	ds_read_b128 v[224:227], v208 offset:64
	ds_read_b128 v[228:231], v208 offset:4416
	ds_read_b128 v[2:5], v208 offset:128
	ds_read_b128 v[6:9], v208 offset:4480
	ds_read_b128 v[10:13], v208 offset:192
	ds_read_b128 v[14:17], v208 offset:4544
	s_waitcnt lgkmcnt(6)
	v_mfma_f32_16x16x32_bf16 v[232:235], v[216:219], v[82:85], 0
	v_mfma_f32_16x16x32_bf16 v[236:239], v[220:223], v[82:85], 0
	s_waitcnt lgkmcnt(4)
	v_mfma_f32_16x16x32_bf16 v[232:235], v[224:227], v[86:89], v[232:235]
	v_mfma_f32_16x16x32_bf16 v[236:239], v[228:231], v[86:89], v[236:239]
	s_waitcnt lgkmcnt(2)
	v_mfma_f32_16x16x32_bf16 v[232:235], v[2:5], v[90:93], v[232:235]
	v_mfma_f32_16x16x32_bf16 v[236:239], v[6:9], v[90:93], v[236:239]
	s_waitcnt lgkmcnt(0)
	v_mfma_f32_16x16x32_bf16 v[232:235], v[10:13], v[94:97], v[232:235]
	v_mfma_f32_16x16x32_bf16 v[236:239], v[14:17], v[94:97], v[236:239]
	s_nop 7
	global_store_dword v[240:241], v232, off offset:-4096
	global_store_dword v[240:241], v233, off
	global_store_dword v[242:243], v234, off offset:-4096
	global_store_dword v[242:243], v235, off
	global_store_dword v[244:245], v236, off offset:-4096
	global_store_dword v[244:245], v237, off
	global_store_dword v[246:247], v238, off offset:-4096
	global_store_dword v[246:247], v239, off
